# gemm_out: one static s_setprio 1 for the blocks dispatched second on each CU (blockIdx >= 256) for the whole phase, reset at phase exit
# baseline (speedup 1.0000x reference)
.LBB0_1347:
	s_nop 0
	v_readlane_b32 s4, v255, 45
	v_readlane_b32 s5, v255, 46
	s_and_b64 vcc, exec, s[4:5]
	s_cbranch_vccz .LBB0_1482
	v_readlane_b32 s4, v254, 49
	v_readlane_b32 s5, v254, 50
	v_mov_b32_e32 v0, v171
	s_andn2_b64 vcc, exec, s[4:5]
	s_cbranch_vccnz .LBB0_1481
	v_lshrrev_b32_e32 v1, 4, v0
	v_bfe_u32 v3, v0, 1, 3
	v_and_b32_e32 v148, 15, v0
	v_ashrrev_i32_e32 v149, 3, v0
	v_bfe_u32 v2, v0, 4, 2
	v_bitop3_b32 v1, v1, v3, 3 bitop3:0x6c
	v_lshlrev_b32_e32 v3, 3, v0
	v_ashrrev_i32_e32 v4, 7, v0
	v_bfe_u32 v5, v0, 6, 1
	v_lshlrev_b32_e32 v0, 4, v0
	v_readlane_b32 s4, v255, 43
	v_and_b32_e32 v168, 0x70, v0
	v_lshlrev_b32_e32 v0, 2, v149
	v_readlane_b32 s5, v255, 44
	s_mov_b32 s6, s4
	s_ashr_i32 s7, s4, 31
	v_bitop3_b32 v0, v0, 56, v3 bitop3:0x48
	s_lshl_b64 s[4:5], s[6:7], 23
	v_readlane_b32 s0, v254, 43
	v_lshlrev_b32_e32 v0, 1, v0
	s_add_u32 s4, s0, s4
	v_readlane_b32 s0, v254, 44
	v_lshl_or_b32 v150, v149, 7, v0
	v_lshlrev_b32_e32 v0, 7, v148
	s_addc_u32 s5, s0, s5
	v_lshl_or_b32 v3, v5, 13, v0
	v_lshl_or_b32 v0, v4, 13, v0
	v_lshlrev_b32_e32 v1, 4, v1
	v_lshl_add_u64 v[128:129], s[4:5], 0, v[168:169]
	v_readlane_b32 s4, v254, 12
	v_or_b32_e32 v151, v3, v1
	v_or_b32_e32 v152, v0, v1
	v_xor_b32_e32 v1, 64, v1
	s_add_i32 s0, s22, 5
	v_readlane_b32 s5, v254, 13
	v_or_b32_e32 v154, v0, v1
	v_lshlrev_b32_e32 v0, 2, v2
	s_cmp_gt_u32 s0, 12
	v_lshl_add_u64 v[130:131], s[4:5], 0, v[168:169]
	v_or_b32_e32 v153, v3, v1
	v_lshl_or_b32 v155, v5, 6, v0
	v_lshlrev_b32_e32 v156, 6, v4
	s_cselect_b64 s[46:47], -1, 0
	s_mul_hi_i32 s49, s6, 5
	s_mul_i32 s48, s6, 5
	s_mov_b32 s6, 0
	v_readlane_b32 s4, v255, 41
	s_nop 0
	s_cmpk_lt_u32 s4, 0x100
	s_cbranch_scc1 .Lgout_noprio
	s_setprio 1
.Lgout_noprio:
	v_readlane_b32 s0, v254, 48
	s_branch .LBB0_1352

.LBB0_1481:
	s_mov_b64 s[6:7], 0
	s_setprio 0
